# v20 + streaming (nt) hint on the 14 single-use LDS-DMA tile loads of the RWKV mixer
# baseline (speedup 1.0000x reference)
.LBB0_434:
	v_cndmask_b32_e64 v0, 0, 1, s[30:31]
	v_cmp_ne_u32_e64 s[10:11], 1, v0
	s_andn2_b64 vcc, exec, s[30:31]
	s_waitcnt lgkmcnt(0)
	s_barrier
	s_cbranch_vccnz .LBB0_455
	s_add_i32 s12, s66, 1
	s_cmp_ge_u32 s12, s59
	s_cbranch_scc1 .LBB0_439
	v_readlane_b32 s100, v252, 33
	v_readlane_b32 s101, v252, 34
	v_readlane_b32 s12, v252, 42
	v_readlane_b32 s14, v252, 40
	v_readlane_b32 s15, v252, 41
	s_nop 3
	s_lshl_b32 s98, s42, 10
	s_add_u32 s98, s34, s98
	s_addc_u32 s99, s35, 0
	s_add_i32 vcc_lo, s42, 1
	s_lshl_b32 vcc_lo, vcc_lo, 9
	s_add_u32 s100, s100, vcc_lo
	s_addc_u32 s101, s101, 0
	s_add_i32 m0, s12, 0x18600
	s_nop 0
	global_load_lds_dwordx4 v224, s[98:99] nt
	s_add_i32 m0, s12, 0x19600
	s_nop 0
	global_load_lds_dwordx4 v225, s[98:99] nt
	s_add_i32 m0, s12, 0x1a600
	s_nop 0
	global_load_lds_dwordx4 v226, s[98:99] nt
	s_add_i32 m0, s12, 0x1b600
	s_nop 0
	global_load_lds_dwordx4 v227, s[98:99] nt
	s_andn2_b64 vcc, exec, s[14:15]
	s_cbranch_vccnz .Lrw_dma_a5
	s_add_i32 m0, s12, 0x1c600
	s_nop 0
	global_load_lds_dwordx4 v228, s[98:99] nt
.Lrw_dma_a5:
	s_add_i32 m0, s12, 0x1ca00
	s_nop 0
	global_load_lds_dwordx4 v229, s[100:101] nt
	s_add_i32 m0, s12, 0x1da00
	s_nop 0
	global_load_lds_dwordx4 v242, s[100:101] nt

.LBB0_536:
	s_and_b64 vcc, exec, s[10:11]
	s_mov_b64 s[10:11], -1
	s_cbranch_vccnz .LBB0_567
	s_add_i32 s10, s66, 1
	v_mov_b32_e32 v46, v161
	s_cmp_ge_u32 s10, s59
	s_cbranch_scc1 .LBB0_540
	v_readlane_b32 s100, v252, 29
	v_readlane_b32 s101, v252, 30
	v_readlane_b32 s10, v252, 42
	v_readlane_b32 s12, v252, 40
	v_readlane_b32 s13, v252, 41
	s_nop 3
	s_mul_i32 s98, s42, 0x2200
	s_add_u32 s100, s100, s98
	s_addc_u32 s101, s101, 0
	s_add_u32 s100, s100, s92
	s_addc_u32 s101, s101, s93
	s_add_u32 s100, s100, 0x1200
	s_addc_u32 s101, s101, 0
	s_add_i32 m0, s10, 0x12000
	s_nop 0
	global_load_lds_dwordx4 v243, s[100:101] nt
	s_add_i32 m0, s10, 0x13000
	s_nop 0
	global_load_lds_dwordx4 v244, s[100:101] nt
	s_add_i32 m0, s10, 0x14000
	s_nop 0
	global_load_lds_dwordx4 v245, s[100:101] nt
	s_add_i32 m0, s10, 0x15000
	s_nop 0
	global_load_lds_dwordx4 v246, s[100:101] nt
	s_add_i32 m0, s10, 0x16000
	s_nop 0
	global_load_lds_dwordx4 v247, s[100:101] nt
	s_add_i32 m0, s10, 0x17000
	s_nop 0
	global_load_lds_dwordx4 v248, s[100:101] nt
	s_andn2_b64 vcc, exec, s[12:13]
	s_cbranch_vccnz .LBB0_540
	s_add_i32 m0, s10, 0x18000
	s_nop 0
	global_load_lds_dwordx4 v249, s[100:101] nt
